# prune write pass: one VALU between v_cmpx and the masked ds_write
# baseline (speedup 1.0000x reference)
.Lp2apr0_iter:
	v_sub_u32_e32 v38, v35, v34
	v_or_b32_e32 v41, 1, v38
	v_ffbh_u32_e32 v41, v41
	v_sub_u32_e32 v41, 26, v41
	v_max_i32_e32 v39, 0, v41
	v_mov_b32_e32 v36, 0
	v_or_b32_e32 v42, 32, v36
	v_lshlrev_b32_e32 v41, v39, v42
	v_add_u32_e64 v43, v34, v41 clamp
	v_mov_b32_e32 v44, 0
	v_cmp_ge_u32_e32 vcc, v0, v43
	v_cmp_ge_u32_e64 s[0:1], v1, v43
	v_cmp_ge_u32_e64 s[2:3], v2, v43
	v_addc_co_u32_e64 v44, vcc, 0, v44, vcc
	v_cmp_ge_u32_e32 vcc, v3, v43
	v_addc_co_u32_e64 v44, s[0:1], 0, v44, s[0:1]
	v_cmp_ge_u32_e64 s[0:1], v4, v43
	v_addc_co_u32_e64 v44, s[2:3], 0, v44, s[2:3]
	v_cmp_ge_u32_e64 s[2:3], v5, v43
	v_addc_co_u32_e64 v44, vcc, 0, v44, vcc
	v_cmp_ge_u32_e32 vcc, v6, v43
	v_addc_co_u32_e64 v44, s[0:1], 0, v44, s[0:1]
	v_cmp_ge_u32_e64 s[0:1], v7, v43
	v_addc_co_u32_e64 v44, s[2:3], 0, v44, s[2:3]
	v_cmp_ge_u32_e64 s[2:3], v8, v43
	v_addc_co_u32_e64 v44, vcc, 0, v44, vcc
	v_cmp_ge_u32_e32 vcc, v9, v43
	v_addc_co_u32_e64 v44, s[0:1], 0, v44, s[0:1]
	v_cmp_ge_u32_e64 s[0:1], v10, v43
	v_addc_co_u32_e64 v44, s[2:3], 0, v44, s[2:3]
	v_cmp_ge_u32_e64 s[2:3], v11, v43
	v_addc_co_u32_e64 v44, vcc, 0, v44, vcc
	v_cmp_ge_u32_e32 vcc, v12, v43
	v_addc_co_u32_e64 v44, s[0:1], 0, v44, s[0:1]
	v_cmp_ge_u32_e64 s[0:1], v13, v43
	v_addc_co_u32_e64 v44, s[2:3], 0, v44, s[2:3]
	v_cmp_ge_u32_e64 s[2:3], v14, v43
	v_addc_co_u32_e64 v44, vcc, 0, v44, vcc
	v_cmp_ge_u32_e32 vcc, v15, v43
	v_addc_co_u32_e64 v44, s[0:1], 0, v44, s[0:1]
	v_cmp_ge_u32_e64 s[0:1], v16, v43
	v_addc_co_u32_e64 v44, s[2:3], 0, v44, s[2:3]
	v_cmp_ge_u32_e64 s[2:3], v17, v43
	v_addc_co_u32_e64 v44, vcc, 0, v44, vcc
	v_cmp_ge_u32_e32 vcc, v18, v43
	v_addc_co_u32_e64 v44, s[0:1], 0, v44, s[0:1]
	v_cmp_ge_u32_e64 s[0:1], v19, v43
	v_addc_co_u32_e64 v44, s[2:3], 0, v44, s[2:3]
	v_cmp_ge_u32_e64 s[2:3], v20, v43
	v_addc_co_u32_e64 v44, vcc, 0, v44, vcc
	v_cmp_ge_u32_e32 vcc, v21, v43
	v_addc_co_u32_e64 v44, s[0:1], 0, v44, s[0:1]
	v_cmp_ge_u32_e64 s[0:1], v22, v43
	v_addc_co_u32_e64 v44, s[2:3], 0, v44, s[2:3]
	v_cmp_ge_u32_e64 s[2:3], v23, v43
	v_addc_co_u32_e64 v44, vcc, 0, v44, vcc
	v_cmp_ge_u32_e32 vcc, v24, v43
	v_addc_co_u32_e64 v44, s[0:1], 0, v44, s[0:1]
	v_cmp_ge_u32_e64 s[0:1], v25, v43
	v_addc_co_u32_e64 v44, s[2:3], 0, v44, s[2:3]
	v_cmp_ge_u32_e64 s[2:3], v26, v43
	v_addc_co_u32_e64 v44, vcc, 0, v44, vcc
	v_cmp_ge_u32_e32 vcc, v27, v43
	v_addc_co_u32_e64 v44, s[0:1], 0, v44, s[0:1]
	v_cmp_ge_u32_e64 s[0:1], v28, v43
	v_addc_co_u32_e64 v44, s[2:3], 0, v44, s[2:3]
	v_cmp_ge_u32_e64 s[2:3], v29, v43
	v_addc_co_u32_e64 v44, vcc, 0, v44, vcc
	v_cmp_ge_u32_e32 vcc, v30, v43
	v_addc_co_u32_e64 v44, s[0:1], 0, v44, s[0:1]
	v_cmp_ge_u32_e64 s[0:1], v31, v43
	v_addc_co_u32_e64 v44, s[2:3], 0, v44, s[2:3]
	v_addc_co_u32_e64 v44, vcc, 0, v44, vcc
	v_addc_co_u32_e64 v44, s[0:1], 0, v44, s[0:1]
	v_mov_b32_e32 v45, v44
	s_nop 1
	v_add_u32_dpp v45, v45, v45 row_ror:1 row_mask:0xf bank_mask:0xf
	s_nop 1
	v_add_u32_dpp v45, v45, v45 row_ror:2 row_mask:0xf bank_mask:0xf
	s_nop 1
	v_add_u32_dpp v45, v45, v45 row_ror:4 row_mask:0xf bank_mask:0xf
	s_nop 1
	v_add_u32_dpp v45, v45, v45 row_ror:8 row_mask:0xf bank_mask:0xf
	s_nop 0
	v_cmp_le_u32_e32 vcc, 0x100, v45
	s_nop 1
	v_cndmask_b32_e32 v36, v36, v42, vcc
	v_cndmask_b32_e32 v46, v46, v45, vcc
	v_cndmask_b32_e32 v47, v47, v44, vcc
	v_or_b32_e32 v42, 16, v36
	v_lshlrev_b32_e32 v41, v39, v42
	v_add_u32_e64 v43, v34, v41 clamp
	v_mov_b32_e32 v44, 0
	v_cmp_ge_u32_e32 vcc, v0, v43
	v_cmp_ge_u32_e64 s[0:1], v1, v43
	v_cmp_ge_u32_e64 s[2:3], v2, v43
	v_addc_co_u32_e64 v44, vcc, 0, v44, vcc
	v_cmp_ge_u32_e32 vcc, v3, v43
	v_addc_co_u32_e64 v44, s[0:1], 0, v44, s[0:1]
	v_cmp_ge_u32_e64 s[0:1], v4, v43
	v_addc_co_u32_e64 v44, s[2:3], 0, v44, s[2:3]
	v_cmp_ge_u32_e64 s[2:3], v5, v43
	v_addc_co_u32_e64 v44, vcc, 0, v44, vcc
	v_cmp_ge_u32_e32 vcc, v6, v43
	v_addc_co_u32_e64 v44, s[0:1], 0, v44, s[0:1]
	v_cmp_ge_u32_e64 s[0:1], v7, v43
	v_addc_co_u32_e64 v44, s[2:3], 0, v44, s[2:3]
	v_cmp_ge_u32_e64 s[2:3], v8, v43
	v_addc_co_u32_e64 v44, vcc, 0, v44, vcc
	v_cmp_ge_u32_e32 vcc, v9, v43
	v_addc_co_u32_e64 v44, s[0:1], 0, v44, s[0:1]
	v_cmp_ge_u32_e64 s[0:1], v10, v43
	v_addc_co_u32_e64 v44, s[2:3], 0, v44, s[2:3]
	v_cmp_ge_u32_e64 s[2:3], v11, v43
	v_addc_co_u32_e64 v44, vcc, 0, v44, vcc
	v_cmp_ge_u32_e32 vcc, v12, v43
	v_addc_co_u32_e64 v44, s[0:1], 0, v44, s[0:1]
	v_cmp_ge_u32_e64 s[0:1], v13, v43
	v_addc_co_u32_e64 v44, s[2:3], 0, v44, s[2:3]
	v_cmp_ge_u32_e64 s[2:3], v14, v43
	v_addc_co_u32_e64 v44, vcc, 0, v44, vcc
	v_cmp_ge_u32_e32 vcc, v15, v43
	v_addc_co_u32_e64 v44, s[0:1], 0, v44, s[0:1]
	v_cmp_ge_u32_e64 s[0:1], v16, v43
	v_addc_co_u32_e64 v44, s[2:3], 0, v44, s[2:3]
	v_cmp_ge_u32_e64 s[2:3], v17, v43
	v_addc_co_u32_e64 v44, vcc, 0, v44, vcc
	v_cmp_ge_u32_e32 vcc, v18, v43
	v_addc_co_u32_e64 v44, s[0:1], 0, v44, s[0:1]
	v_cmp_ge_u32_e64 s[0:1], v19, v43
	v_addc_co_u32_e64 v44, s[2:3], 0, v44, s[2:3]
	v_cmp_ge_u32_e64 s[2:3], v20, v43
	v_addc_co_u32_e64 v44, vcc, 0, v44, vcc
	v_cmp_ge_u32_e32 vcc, v21, v43
	v_addc_co_u32_e64 v44, s[0:1], 0, v44, s[0:1]
	v_cmp_ge_u32_e64 s[0:1], v22, v43
	v_addc_co_u32_e64 v44, s[2:3], 0, v44, s[2:3]
	v_cmp_ge_u32_e64 s[2:3], v23, v43
	v_addc_co_u32_e64 v44, vcc, 0, v44, vcc
	v_cmp_ge_u32_e32 vcc, v24, v43
	v_addc_co_u32_e64 v44, s[0:1], 0, v44, s[0:1]
	v_cmp_ge_u32_e64 s[0:1], v25, v43
	v_addc_co_u32_e64 v44, s[2:3], 0, v44, s[2:3]
	v_cmp_ge_u32_e64 s[2:3], v26, v43
	v_addc_co_u32_e64 v44, vcc, 0, v44, vcc
	v_cmp_ge_u32_e32 vcc, v27, v43
	v_addc_co_u32_e64 v44, s[0:1], 0, v44, s[0:1]
	v_cmp_ge_u32_e64 s[0:1], v28, v43
	v_addc_co_u32_e64 v44, s[2:3], 0, v44, s[2:3]
	v_cmp_ge_u32_e64 s[2:3], v29, v43
	v_addc_co_u32_e64 v44, vcc, 0, v44, vcc
	v_cmp_ge_u32_e32 vcc, v30, v43
	v_addc_co_u32_e64 v44, s[0:1], 0, v44, s[0:1]
	v_cmp_ge_u32_e64 s[0:1], v31, v43
	v_addc_co_u32_e64 v44, s[2:3], 0, v44, s[2:3]
	v_addc_co_u32_e64 v44, vcc, 0, v44, vcc
	v_addc_co_u32_e64 v44, s[0:1], 0, v44, s[0:1]
	v_mov_b32_e32 v45, v44
	s_nop 1
	v_add_u32_dpp v45, v45, v45 row_ror:1 row_mask:0xf bank_mask:0xf
	s_nop 1
	v_add_u32_dpp v45, v45, v45 row_ror:2 row_mask:0xf bank_mask:0xf
	s_nop 1
	v_add_u32_dpp v45, v45, v45 row_ror:4 row_mask:0xf bank_mask:0xf
	s_nop 1
	v_add_u32_dpp v45, v45, v45 row_ror:8 row_mask:0xf bank_mask:0xf
	s_nop 0
	v_cmp_le_u32_e32 vcc, 0x100, v45
	s_nop 1
	v_cndmask_b32_e32 v36, v36, v42, vcc
	v_cndmask_b32_e32 v46, v46, v45, vcc
	v_cndmask_b32_e32 v47, v47, v44, vcc
	v_or_b32_e32 v42, 8, v36
	v_lshlrev_b32_e32 v41, v39, v42
	v_add_u32_e64 v43, v34, v41 clamp
	v_mov_b32_e32 v44, 0
	v_cmp_ge_u32_e32 vcc, v0, v43
	v_cmp_ge_u32_e64 s[0:1], v1, v43
	v_cmp_ge_u32_e64 s[2:3], v2, v43
	v_addc_co_u32_e64 v44, vcc, 0, v44, vcc
	v_cmp_ge_u32_e32 vcc, v3, v43
	v_addc_co_u32_e64 v44, s[0:1], 0, v44, s[0:1]
	v_cmp_ge_u32_e64 s[0:1], v4, v43
	v_addc_co_u32_e64 v44, s[2:3], 0, v44, s[2:3]
	v_cmp_ge_u32_e64 s[2:3], v5, v43
	v_addc_co_u32_e64 v44, vcc, 0, v44, vcc
	v_cmp_ge_u32_e32 vcc, v6, v43
	v_addc_co_u32_e64 v44, s[0:1], 0, v44, s[0:1]
	v_cmp_ge_u32_e64 s[0:1], v7, v43
	v_addc_co_u32_e64 v44, s[2:3], 0, v44, s[2:3]
	v_cmp_ge_u32_e64 s[2:3], v8, v43
	v_addc_co_u32_e64 v44, vcc, 0, v44, vcc
	v_cmp_ge_u32_e32 vcc, v9, v43
	v_addc_co_u32_e64 v44, s[0:1], 0, v44, s[0:1]
	v_cmp_ge_u32_e64 s[0:1], v10, v43
	v_addc_co_u32_e64 v44, s[2:3], 0, v44, s[2:3]
	v_cmp_ge_u32_e64 s[2:3], v11, v43
	v_addc_co_u32_e64 v44, vcc, 0, v44, vcc
	v_cmp_ge_u32_e32 vcc, v12, v43
	v_addc_co_u32_e64 v44, s[0:1], 0, v44, s[0:1]
	v_cmp_ge_u32_e64 s[0:1], v13, v43
	v_addc_co_u32_e64 v44, s[2:3], 0, v44, s[2:3]
	v_cmp_ge_u32_e64 s[2:3], v14, v43
	v_addc_co_u32_e64 v44, vcc, 0, v44, vcc
	v_cmp_ge_u32_e32 vcc, v15, v43
	v_addc_co_u32_e64 v44, s[0:1], 0, v44, s[0:1]
	v_cmp_ge_u32_e64 s[0:1], v16, v43
	v_addc_co_u32_e64 v44, s[2:3], 0, v44, s[2:3]
	v_cmp_ge_u32_e64 s[2:3], v17, v43
	v_addc_co_u32_e64 v44, vcc, 0, v44, vcc
	v_cmp_ge_u32_e32 vcc, v18, v43
	v_addc_co_u32_e64 v44, s[0:1], 0, v44, s[0:1]
	v_cmp_ge_u32_e64 s[0:1], v19, v43
	v_addc_co_u32_e64 v44, s[2:3], 0, v44, s[2:3]
	v_cmp_ge_u32_e64 s[2:3], v20, v43
	v_addc_co_u32_e64 v44, vcc, 0, v44, vcc
	v_cmp_ge_u32_e32 vcc, v21, v43
	v_addc_co_u32_e64 v44, s[0:1], 0, v44, s[0:1]
	v_cmp_ge_u32_e64 s[0:1], v22, v43
	v_addc_co_u32_e64 v44, s[2:3], 0, v44, s[2:3]
	v_cmp_ge_u32_e64 s[2:3], v23, v43
	v_addc_co_u32_e64 v44, vcc, 0, v44, vcc
	v_cmp_ge_u32_e32 vcc, v24, v43
	v_addc_co_u32_e64 v44, s[0:1], 0, v44, s[0:1]
	v_cmp_ge_u32_e64 s[0:1], v25, v43
	v_addc_co_u32_e64 v44, s[2:3], 0, v44, s[2:3]
	v_cmp_ge_u32_e64 s[2:3], v26, v43
	v_addc_co_u32_e64 v44, vcc, 0, v44, vcc
	v_cmp_ge_u32_e32 vcc, v27, v43
	v_addc_co_u32_e64 v44, s[0:1], 0, v44, s[0:1]
	v_cmp_ge_u32_e64 s[0:1], v28, v43
	v_addc_co_u32_e64 v44, s[2:3], 0, v44, s[2:3]
	v_cmp_ge_u32_e64 s[2:3], v29, v43
	v_addc_co_u32_e64 v44, vcc, 0, v44, vcc
	v_cmp_ge_u32_e32 vcc, v30, v43
	v_addc_co_u32_e64 v44, s[0:1], 0, v44, s[0:1]
	v_cmp_ge_u32_e64 s[0:1], v31, v43
	v_addc_co_u32_e64 v44, s[2:3], 0, v44, s[2:3]
	v_addc_co_u32_e64 v44, vcc, 0, v44, vcc
	v_addc_co_u32_e64 v44, s[0:1], 0, v44, s[0:1]
	v_mov_b32_e32 v45, v44
	s_nop 1
	v_add_u32_dpp v45, v45, v45 row_ror:1 row_mask:0xf bank_mask:0xf
	s_nop 1
	v_add_u32_dpp v45, v45, v45 row_ror:2 row_mask:0xf bank_mask:0xf
	s_nop 1
	v_add_u32_dpp v45, v45, v45 row_ror:4 row_mask:0xf bank_mask:0xf
	s_nop 1
	v_add_u32_dpp v45, v45, v45 row_ror:8 row_mask:0xf bank_mask:0xf
	s_nop 0
	v_cmp_le_u32_e32 vcc, 0x100, v45
	s_nop 1
	v_cndmask_b32_e32 v36, v36, v42, vcc
	v_cndmask_b32_e32 v46, v46, v45, vcc
	v_cndmask_b32_e32 v47, v47, v44, vcc
	v_or_b32_e32 v42, 4, v36
	v_lshlrev_b32_e32 v41, v39, v42
	v_add_u32_e64 v43, v34, v41 clamp
	v_mov_b32_e32 v44, 0
	v_cmp_ge_u32_e32 vcc, v0, v43
	v_cmp_ge_u32_e64 s[0:1], v1, v43
	v_cmp_ge_u32_e64 s[2:3], v2, v43
	v_addc_co_u32_e64 v44, vcc, 0, v44, vcc
	v_cmp_ge_u32_e32 vcc, v3, v43
	v_addc_co_u32_e64 v44, s[0:1], 0, v44, s[0:1]
	v_cmp_ge_u32_e64 s[0:1], v4, v43
	v_addc_co_u32_e64 v44, s[2:3], 0, v44, s[2:3]
	v_cmp_ge_u32_e64 s[2:3], v5, v43
	v_addc_co_u32_e64 v44, vcc, 0, v44, vcc
	v_cmp_ge_u32_e32 vcc, v6, v43
	v_addc_co_u32_e64 v44, s[0:1], 0, v44, s[0:1]
	v_cmp_ge_u32_e64 s[0:1], v7, v43
	v_addc_co_u32_e64 v44, s[2:3], 0, v44, s[2:3]
	v_cmp_ge_u32_e64 s[2:3], v8, v43
	v_addc_co_u32_e64 v44, vcc, 0, v44, vcc
	v_cmp_ge_u32_e32 vcc, v9, v43
	v_addc_co_u32_e64 v44, s[0:1], 0, v44, s[0:1]
	v_cmp_ge_u32_e64 s[0:1], v10, v43
	v_addc_co_u32_e64 v44, s[2:3], 0, v44, s[2:3]
	v_cmp_ge_u32_e64 s[2:3], v11, v43
	v_addc_co_u32_e64 v44, vcc, 0, v44, vcc
	v_cmp_ge_u32_e32 vcc, v12, v43
	v_addc_co_u32_e64 v44, s[0:1], 0, v44, s[0:1]
	v_cmp_ge_u32_e64 s[0:1], v13, v43
	v_addc_co_u32_e64 v44, s[2:3], 0, v44, s[2:3]
	v_cmp_ge_u32_e64 s[2:3], v14, v43
	v_addc_co_u32_e64 v44, vcc, 0, v44, vcc
	v_cmp_ge_u32_e32 vcc, v15, v43
	v_addc_co_u32_e64 v44, s[0:1], 0, v44, s[0:1]
	v_cmp_ge_u32_e64 s[0:1], v16, v43
	v_addc_co_u32_e64 v44, s[2:3], 0, v44, s[2:3]
	v_cmp_ge_u32_e64 s[2:3], v17, v43
	v_addc_co_u32_e64 v44, vcc, 0, v44, vcc
	v_cmp_ge_u32_e32 vcc, v18, v43
	v_addc_co_u32_e64 v44, s[0:1], 0, v44, s[0:1]
	v_cmp_ge_u32_e64 s[0:1], v19, v43
	v_addc_co_u32_e64 v44, s[2:3], 0, v44, s[2:3]
	v_cmp_ge_u32_e64 s[2:3], v20, v43
	v_addc_co_u32_e64 v44, vcc, 0, v44, vcc
	v_cmp_ge_u32_e32 vcc, v21, v43
	v_addc_co_u32_e64 v44, s[0:1], 0, v44, s[0:1]
	v_cmp_ge_u32_e64 s[0:1], v22, v43
	v_addc_co_u32_e64 v44, s[2:3], 0, v44, s[2:3]
	v_cmp_ge_u32_e64 s[2:3], v23, v43
	v_addc_co_u32_e64 v44, vcc, 0, v44, vcc
	v_cmp_ge_u32_e32 vcc, v24, v43
	v_addc_co_u32_e64 v44, s[0:1], 0, v44, s[0:1]
	v_cmp_ge_u32_e64 s[0:1], v25, v43
	v_addc_co_u32_e64 v44, s[2:3], 0, v44, s[2:3]
	v_cmp_ge_u32_e64 s[2:3], v26, v43
	v_addc_co_u32_e64 v44, vcc, 0, v44, vcc
	v_cmp_ge_u32_e32 vcc, v27, v43
	v_addc_co_u32_e64 v44, s[0:1], 0, v44, s[0:1]
	v_cmp_ge_u32_e64 s[0:1], v28, v43
	v_addc_co_u32_e64 v44, s[2:3], 0, v44, s[2:3]
	v_cmp_ge_u32_e64 s[2:3], v29, v43
	v_addc_co_u32_e64 v44, vcc, 0, v44, vcc
	v_cmp_ge_u32_e32 vcc, v30, v43
	v_addc_co_u32_e64 v44, s[0:1], 0, v44, s[0:1]
	v_cmp_ge_u32_e64 s[0:1], v31, v43
	v_addc_co_u32_e64 v44, s[2:3], 0, v44, s[2:3]
	v_addc_co_u32_e64 v44, vcc, 0, v44, vcc
	v_addc_co_u32_e64 v44, s[0:1], 0, v44, s[0:1]
	v_mov_b32_e32 v45, v44
	s_nop 1
	v_add_u32_dpp v45, v45, v45 row_ror:1 row_mask:0xf bank_mask:0xf
	s_nop 1
	v_add_u32_dpp v45, v45, v45 row_ror:2 row_mask:0xf bank_mask:0xf
	s_nop 1
	v_add_u32_dpp v45, v45, v45 row_ror:4 row_mask:0xf bank_mask:0xf
	s_nop 1
	v_add_u32_dpp v45, v45, v45 row_ror:8 row_mask:0xf bank_mask:0xf
	s_nop 0
	v_cmp_le_u32_e32 vcc, 0x100, v45
	s_nop 1
	v_cndmask_b32_e32 v36, v36, v42, vcc
	v_cndmask_b32_e32 v46, v46, v45, vcc
	v_cndmask_b32_e32 v47, v47, v44, vcc
	v_or_b32_e32 v42, 2, v36
	v_lshlrev_b32_e32 v41, v39, v42
	v_add_u32_e64 v43, v34, v41 clamp
	v_mov_b32_e32 v44, 0
	v_cmp_ge_u32_e32 vcc, v0, v43
	v_cmp_ge_u32_e64 s[0:1], v1, v43
	v_cmp_ge_u32_e64 s[2:3], v2, v43
	v_addc_co_u32_e64 v44, vcc, 0, v44, vcc
	v_cmp_ge_u32_e32 vcc, v3, v43
	v_addc_co_u32_e64 v44, s[0:1], 0, v44, s[0:1]
	v_cmp_ge_u32_e64 s[0:1], v4, v43
	v_addc_co_u32_e64 v44, s[2:3], 0, v44, s[2:3]
	v_cmp_ge_u32_e64 s[2:3], v5, v43
	v_addc_co_u32_e64 v44, vcc, 0, v44, vcc
	v_cmp_ge_u32_e32 vcc, v6, v43
	v_addc_co_u32_e64 v44, s[0:1], 0, v44, s[0:1]
	v_cmp_ge_u32_e64 s[0:1], v7, v43
	v_addc_co_u32_e64 v44, s[2:3], 0, v44, s[2:3]
	v_cmp_ge_u32_e64 s[2:3], v8, v43
	v_addc_co_u32_e64 v44, vcc, 0, v44, vcc
	v_cmp_ge_u32_e32 vcc, v9, v43
	v_addc_co_u32_e64 v44, s[0:1], 0, v44, s[0:1]
	v_cmp_ge_u32_e64 s[0:1], v10, v43
	v_addc_co_u32_e64 v44, s[2:3], 0, v44, s[2:3]
	v_cmp_ge_u32_e64 s[2:3], v11, v43
	v_addc_co_u32_e64 v44, vcc, 0, v44, vcc
	v_cmp_ge_u32_e32 vcc, v12, v43
	v_addc_co_u32_e64 v44, s[0:1], 0, v44, s[0:1]
	v_cmp_ge_u32_e64 s[0:1], v13, v43
	v_addc_co_u32_e64 v44, s[2:3], 0, v44, s[2:3]
	v_cmp_ge_u32_e64 s[2:3], v14, v43
	v_addc_co_u32_e64 v44, vcc, 0, v44, vcc
	v_cmp_ge_u32_e32 vcc, v15, v43
	v_addc_co_u32_e64 v44, s[0:1], 0, v44, s[0:1]
	v_cmp_ge_u32_e64 s[0:1], v16, v43
	v_addc_co_u32_e64 v44, s[2:3], 0, v44, s[2:3]
	v_cmp_ge_u32_e64 s[2:3], v17, v43
	v_addc_co_u32_e64 v44, vcc, 0, v44, vcc
	v_cmp_ge_u32_e32 vcc, v18, v43
	v_addc_co_u32_e64 v44, s[0:1], 0, v44, s[0:1]
	v_cmp_ge_u32_e64 s[0:1], v19, v43
	v_addc_co_u32_e64 v44, s[2:3], 0, v44, s[2:3]
	v_cmp_ge_u32_e64 s[2:3], v20, v43
	v_addc_co_u32_e64 v44, vcc, 0, v44, vcc
	v_cmp_ge_u32_e32 vcc, v21, v43
	v_addc_co_u32_e64 v44, s[0:1], 0, v44, s[0:1]
	v_cmp_ge_u32_e64 s[0:1], v22, v43
	v_addc_co_u32_e64 v44, s[2:3], 0, v44, s[2:3]
	v_cmp_ge_u32_e64 s[2:3], v23, v43
	v_addc_co_u32_e64 v44, vcc, 0, v44, vcc
	v_cmp_ge_u32_e32 vcc, v24, v43
	v_addc_co_u32_e64 v44, s[0:1], 0, v44, s[0:1]
	v_cmp_ge_u32_e64 s[0:1], v25, v43
	v_addc_co_u32_e64 v44, s[2:3], 0, v44, s[2:3]
	v_cmp_ge_u32_e64 s[2:3], v26, v43
	v_addc_co_u32_e64 v44, vcc, 0, v44, vcc
	v_cmp_ge_u32_e32 vcc, v27, v43
	v_addc_co_u32_e64 v44, s[0:1], 0, v44, s[0:1]
	v_cmp_ge_u32_e64 s[0:1], v28, v43
	v_addc_co_u32_e64 v44, s[2:3], 0, v44, s[2:3]
	v_cmp_ge_u32_e64 s[2:3], v29, v43
	v_addc_co_u32_e64 v44, vcc, 0, v44, vcc
	v_cmp_ge_u32_e32 vcc, v30, v43
	v_addc_co_u32_e64 v44, s[0:1], 0, v44, s[0:1]
	v_cmp_ge_u32_e64 s[0:1], v31, v43
	v_addc_co_u32_e64 v44, s[2:3], 0, v44, s[2:3]
	v_addc_co_u32_e64 v44, vcc, 0, v44, vcc
	v_addc_co_u32_e64 v44, s[0:1], 0, v44, s[0:1]
	v_mov_b32_e32 v45, v44
	s_nop 1
	v_add_u32_dpp v45, v45, v45 row_ror:1 row_mask:0xf bank_mask:0xf
	s_nop 1
	v_add_u32_dpp v45, v45, v45 row_ror:2 row_mask:0xf bank_mask:0xf
	s_nop 1
	v_add_u32_dpp v45, v45, v45 row_ror:4 row_mask:0xf bank_mask:0xf
	s_nop 1
	v_add_u32_dpp v45, v45, v45 row_ror:8 row_mask:0xf bank_mask:0xf
	s_nop 0
	v_cmp_le_u32_e32 vcc, 0x100, v45
	s_nop 1
	v_cndmask_b32_e32 v36, v36, v42, vcc
	v_cndmask_b32_e32 v46, v46, v45, vcc
	v_cndmask_b32_e32 v47, v47, v44, vcc
	v_or_b32_e32 v42, 1, v36
	v_lshlrev_b32_e32 v41, v39, v42
	v_add_u32_e64 v43, v34, v41 clamp
	v_mov_b32_e32 v44, 0
	v_cmp_ge_u32_e32 vcc, v0, v43
	v_cmp_ge_u32_e64 s[0:1], v1, v43
	v_cmp_ge_u32_e64 s[2:3], v2, v43
	v_addc_co_u32_e64 v44, vcc, 0, v44, vcc
	v_cmp_ge_u32_e32 vcc, v3, v43
	v_addc_co_u32_e64 v44, s[0:1], 0, v44, s[0:1]
	v_cmp_ge_u32_e64 s[0:1], v4, v43
	v_addc_co_u32_e64 v44, s[2:3], 0, v44, s[2:3]
	v_cmp_ge_u32_e64 s[2:3], v5, v43
	v_addc_co_u32_e64 v44, vcc, 0, v44, vcc
	v_cmp_ge_u32_e32 vcc, v6, v43
	v_addc_co_u32_e64 v44, s[0:1], 0, v44, s[0:1]
	v_cmp_ge_u32_e64 s[0:1], v7, v43
	v_addc_co_u32_e64 v44, s[2:3], 0, v44, s[2:3]
	v_cmp_ge_u32_e64 s[2:3], v8, v43
	v_addc_co_u32_e64 v44, vcc, 0, v44, vcc
	v_cmp_ge_u32_e32 vcc, v9, v43
	v_addc_co_u32_e64 v44, s[0:1], 0, v44, s[0:1]
	v_cmp_ge_u32_e64 s[0:1], v10, v43
	v_addc_co_u32_e64 v44, s[2:3], 0, v44, s[2:3]
	v_cmp_ge_u32_e64 s[2:3], v11, v43
	v_addc_co_u32_e64 v44, vcc, 0, v44, vcc
	v_cmp_ge_u32_e32 vcc, v12, v43
	v_addc_co_u32_e64 v44, s[0:1], 0, v44, s[0:1]
	v_cmp_ge_u32_e64 s[0:1], v13, v43
	v_addc_co_u32_e64 v44, s[2:3], 0, v44, s[2:3]
	v_cmp_ge_u32_e64 s[2:3], v14, v43
	v_addc_co_u32_e64 v44, vcc, 0, v44, vcc
	v_cmp_ge_u32_e32 vcc, v15, v43
	v_addc_co_u32_e64 v44, s[0:1], 0, v44, s[0:1]
	v_cmp_ge_u32_e64 s[0:1], v16, v43
	v_addc_co_u32_e64 v44, s[2:3], 0, v44, s[2:3]
	v_cmp_ge_u32_e64 s[2:3], v17, v43
	v_addc_co_u32_e64 v44, vcc, 0, v44, vcc
	v_cmp_ge_u32_e32 vcc, v18, v43
	v_addc_co_u32_e64 v44, s[0:1], 0, v44, s[0:1]
	v_cmp_ge_u32_e64 s[0:1], v19, v43
	v_addc_co_u32_e64 v44, s[2:3], 0, v44, s[2:3]
	v_cmp_ge_u32_e64 s[2:3], v20, v43
	v_addc_co_u32_e64 v44, vcc, 0, v44, vcc
	v_cmp_ge_u32_e32 vcc, v21, v43
	v_addc_co_u32_e64 v44, s[0:1], 0, v44, s[0:1]
	v_cmp_ge_u32_e64 s[0:1], v22, v43
	v_addc_co_u32_e64 v44, s[2:3], 0, v44, s[2:3]
	v_cmp_ge_u32_e64 s[2:3], v23, v43
	v_addc_co_u32_e64 v44, vcc, 0, v44, vcc
	v_cmp_ge_u32_e32 vcc, v24, v43
	v_addc_co_u32_e64 v44, s[0:1], 0, v44, s[0:1]
	v_cmp_ge_u32_e64 s[0:1], v25, v43
	v_addc_co_u32_e64 v44, s[2:3], 0, v44, s[2:3]
	v_cmp_ge_u32_e64 s[2:3], v26, v43
	v_addc_co_u32_e64 v44, vcc, 0, v44, vcc
	v_cmp_ge_u32_e32 vcc, v27, v43
	v_addc_co_u32_e64 v44, s[0:1], 0, v44, s[0:1]
	v_cmp_ge_u32_e64 s[0:1], v28, v43
	v_addc_co_u32_e64 v44, s[2:3], 0, v44, s[2:3]
	v_cmp_ge_u32_e64 s[2:3], v29, v43
	v_addc_co_u32_e64 v44, vcc, 0, v44, vcc
	v_cmp_ge_u32_e32 vcc, v30, v43
	v_addc_co_u32_e64 v44, s[0:1], 0, v44, s[0:1]
	v_cmp_ge_u32_e64 s[0:1], v31, v43
	v_addc_co_u32_e64 v44, s[2:3], 0, v44, s[2:3]
	v_addc_co_u32_e64 v44, vcc, 0, v44, vcc
	v_addc_co_u32_e64 v44, s[0:1], 0, v44, s[0:1]
	v_mov_b32_e32 v45, v44
	s_nop 1
	v_add_u32_dpp v45, v45, v45 row_ror:1 row_mask:0xf bank_mask:0xf
	s_nop 1
	v_add_u32_dpp v45, v45, v45 row_ror:2 row_mask:0xf bank_mask:0xf
	s_nop 1
	v_add_u32_dpp v45, v45, v45 row_ror:4 row_mask:0xf bank_mask:0xf
	s_nop 1
	v_add_u32_dpp v45, v45, v45 row_ror:8 row_mask:0xf bank_mask:0xf
	s_nop 0
	v_cmp_le_u32_e32 vcc, 0x100, v45
	s_nop 1
	v_cndmask_b32_e32 v36, v36, v42, vcc
	v_cndmask_b32_e32 v46, v46, v45, vcc
	v_cndmask_b32_e32 v47, v47, v44, vcc
	v_lshlrev_b32_e32 v41, v39, v36
	v_add_u32_e32 v41, v34, v41
	v_cmp_ge_u32_e32 vcc, 0x120, v46
	v_cmp_eq_u32_e64 s[0:1], 0, v39
	v_lshlrev_b32_e32 v42, v39, v200
	v_add_u32_e32 v42, -1, v42
	s_or_b64 vcc, vcc, s[0:1]
	s_andn2_b64 s[0:1], vcc, s[50:51]
	s_nor_b64 s[2:3], vcc, s[50:51]
	s_or_b64 s[50:51], s[50:51], vcc
	v_add_u32_e64 v42, v41, v42 clamp
	v_min_u32_e32 v42, v42, v35
	v_cndmask_b32_e64 v37, v37, v41, s[0:1]
	v_cndmask_b32_e64 v62, v62, v47, s[0:1]
	v_cndmask_b32_e64 v35, v35, v42, s[2:3]
	v_cndmask_b32_e64 v34, v34, v41, s[2:3]
	s_cmp_eq_u64 s[50:51], -1
	s_cbranch_scc0 .Lp2apr0_iter
	s_mov_b64 exec, s[22:23]
	v_mov_b32_e32 v61, v62
	s_nop 1
	v_add_u32_dpp v61, v61, v61 row_shr:1 row_mask:0xf bank_mask:0xf bound_ctrl:1
	s_nop 1
	v_add_u32_dpp v61, v61, v61 row_shr:2 row_mask:0xf bank_mask:0xf bound_ctrl:1
	s_nop 1
	v_add_u32_dpp v61, v61, v61 row_shr:4 row_mask:0xf bank_mask:0xf bound_ctrl:1
	s_nop 1
	v_add_u32_dpp v61, v61, v61 row_shr:8 row_mask:0xf bank_mask:0xf bound_ctrl:1
	v_sub_u32_e32 v62, v61, v62
	v_lshl_add_u32 v41, v62, 2, v59
	v_cmpx_ge_u32_e32 vcc, v0, v37
	v_add_u32_e32 v62, 1, v62
	ds_write_b32 v41, v0
	s_mov_b64 exec, s[22:23]
	v_lshl_add_u32 v41, v62, 2, v59
	v_cmpx_ge_u32_e32 vcc, v1, v37
	v_add_u32_e32 v62, 1, v62
	ds_write_b32 v41, v1
	s_mov_b64 exec, s[22:23]
	v_lshl_add_u32 v41, v62, 2, v59
	v_cmpx_ge_u32_e32 vcc, v2, v37
	v_add_u32_e32 v62, 1, v62
	ds_write_b32 v41, v2
	s_mov_b64 exec, s[22:23]
	v_lshl_add_u32 v41, v62, 2, v59
	v_cmpx_ge_u32_e32 vcc, v3, v37
	v_add_u32_e32 v62, 1, v62
	ds_write_b32 v41, v3
	s_mov_b64 exec, s[22:23]
	v_lshl_add_u32 v41, v62, 2, v59
	v_cmpx_ge_u32_e32 vcc, v4, v37
	v_add_u32_e32 v62, 1, v62
	ds_write_b32 v41, v4
	s_mov_b64 exec, s[22:23]
	v_lshl_add_u32 v41, v62, 2, v59
	v_cmpx_ge_u32_e32 vcc, v5, v37
	v_add_u32_e32 v62, 1, v62
	ds_write_b32 v41, v5
	s_mov_b64 exec, s[22:23]
	v_lshl_add_u32 v41, v62, 2, v59
	v_cmpx_ge_u32_e32 vcc, v6, v37
	v_add_u32_e32 v62, 1, v62
	ds_write_b32 v41, v6
	s_mov_b64 exec, s[22:23]
	v_lshl_add_u32 v41, v62, 2, v59
	v_cmpx_ge_u32_e32 vcc, v7, v37
	v_add_u32_e32 v62, 1, v62
	ds_write_b32 v41, v7
	s_mov_b64 exec, s[22:23]
	v_lshl_add_u32 v41, v62, 2, v59
	v_cmpx_ge_u32_e32 vcc, v8, v37
	v_add_u32_e32 v62, 1, v62
	ds_write_b32 v41, v8
	s_mov_b64 exec, s[22:23]
	v_lshl_add_u32 v41, v62, 2, v59
	v_cmpx_ge_u32_e32 vcc, v9, v37
	v_add_u32_e32 v62, 1, v62
	ds_write_b32 v41, v9
	s_mov_b64 exec, s[22:23]
	v_lshl_add_u32 v41, v62, 2, v59
	v_cmpx_ge_u32_e32 vcc, v10, v37
	v_add_u32_e32 v62, 1, v62
	ds_write_b32 v41, v10
	s_mov_b64 exec, s[22:23]
	v_lshl_add_u32 v41, v62, 2, v59
	v_cmpx_ge_u32_e32 vcc, v11, v37
	v_add_u32_e32 v62, 1, v62
	ds_write_b32 v41, v11
	s_mov_b64 exec, s[22:23]
	v_lshl_add_u32 v41, v62, 2, v59
	v_cmpx_ge_u32_e32 vcc, v12, v37
	v_add_u32_e32 v62, 1, v62
	ds_write_b32 v41, v12
	s_mov_b64 exec, s[22:23]
	v_lshl_add_u32 v41, v62, 2, v59
	v_cmpx_ge_u32_e32 vcc, v13, v37
	v_add_u32_e32 v62, 1, v62
	ds_write_b32 v41, v13
	s_mov_b64 exec, s[22:23]
	v_lshl_add_u32 v41, v62, 2, v59
	v_cmpx_ge_u32_e32 vcc, v14, v37
	v_add_u32_e32 v62, 1, v62
	ds_write_b32 v41, v14
	s_mov_b64 exec, s[22:23]
	v_lshl_add_u32 v41, v62, 2, v59
	v_cmpx_ge_u32_e32 vcc, v15, v37
	v_add_u32_e32 v62, 1, v62
	ds_write_b32 v41, v15
	s_mov_b64 exec, s[22:23]
	v_lshl_add_u32 v41, v62, 2, v59
	v_cmpx_ge_u32_e32 vcc, v16, v37
	v_add_u32_e32 v62, 1, v62
	ds_write_b32 v41, v16
	s_mov_b64 exec, s[22:23]
	v_lshl_add_u32 v41, v62, 2, v59
	v_cmpx_ge_u32_e32 vcc, v17, v37
	v_add_u32_e32 v62, 1, v62
	ds_write_b32 v41, v17
	s_mov_b64 exec, s[22:23]
	v_lshl_add_u32 v41, v62, 2, v59
	v_cmpx_ge_u32_e32 vcc, v18, v37
	v_add_u32_e32 v62, 1, v62
	ds_write_b32 v41, v18
	s_mov_b64 exec, s[22:23]
	v_lshl_add_u32 v41, v62, 2, v59
	v_cmpx_ge_u32_e32 vcc, v19, v37
	v_add_u32_e32 v62, 1, v62
	ds_write_b32 v41, v19
	s_mov_b64 exec, s[22:23]
	v_lshl_add_u32 v41, v62, 2, v59
	v_cmpx_ge_u32_e32 vcc, v20, v37
	v_add_u32_e32 v62, 1, v62
	ds_write_b32 v41, v20
	s_mov_b64 exec, s[22:23]
	v_lshl_add_u32 v41, v62, 2, v59
	v_cmpx_ge_u32_e32 vcc, v21, v37
	v_add_u32_e32 v62, 1, v62
	ds_write_b32 v41, v21
	s_mov_b64 exec, s[22:23]
	v_lshl_add_u32 v41, v62, 2, v59
	v_cmpx_ge_u32_e32 vcc, v22, v37
	v_add_u32_e32 v62, 1, v62
	ds_write_b32 v41, v22
	s_mov_b64 exec, s[22:23]
	v_lshl_add_u32 v41, v62, 2, v59
	v_cmpx_ge_u32_e32 vcc, v23, v37
	v_add_u32_e32 v62, 1, v62
	ds_write_b32 v41, v23
	s_mov_b64 exec, s[22:23]
	v_lshl_add_u32 v41, v62, 2, v59
	v_cmpx_ge_u32_e32 vcc, v24, v37
	v_add_u32_e32 v62, 1, v62
	ds_write_b32 v41, v24
	s_mov_b64 exec, s[22:23]
	v_lshl_add_u32 v41, v62, 2, v59
	v_cmpx_ge_u32_e32 vcc, v25, v37
	v_add_u32_e32 v62, 1, v62
	ds_write_b32 v41, v25
	s_mov_b64 exec, s[22:23]
	v_lshl_add_u32 v41, v62, 2, v59
	v_cmpx_ge_u32_e32 vcc, v26, v37
	v_add_u32_e32 v62, 1, v62
	ds_write_b32 v41, v26
	s_mov_b64 exec, s[22:23]
	v_lshl_add_u32 v41, v62, 2, v59
	v_cmpx_ge_u32_e32 vcc, v27, v37
	v_add_u32_e32 v62, 1, v62
	ds_write_b32 v41, v27
	s_mov_b64 exec, s[22:23]
	v_lshl_add_u32 v41, v62, 2, v59
	v_cmpx_ge_u32_e32 vcc, v28, v37
	v_add_u32_e32 v62, 1, v62
	ds_write_b32 v41, v28
	s_mov_b64 exec, s[22:23]
	v_lshl_add_u32 v41, v62, 2, v59
	v_cmpx_ge_u32_e32 vcc, v29, v37
	v_add_u32_e32 v62, 1, v62
	ds_write_b32 v41, v29
	s_mov_b64 exec, s[22:23]
	v_lshl_add_u32 v41, v62, 2, v59
	v_cmpx_ge_u32_e32 vcc, v30, v37
	v_add_u32_e32 v62, 1, v62
	ds_write_b32 v41, v30
	s_mov_b64 exec, s[22:23]
	v_lshl_add_u32 v41, v62, 2, v59
	v_cmpx_ge_u32_e32 vcc, v31, v37
	v_add_u32_e32 v62, 1, v62
	ds_write_b32 v41, v31
	s_mov_b64 exec, s[22:23]
	s_mov_b64 exec, -1
	v_and_b32_e32 v41, 0xffffe000, v37
	v_ashrrev_i32_e32 v42, 31, v41
	v_not_b32_e32 v42, v42
	v_or_b32_e32 v42, 0x80000000, v42
	v_xor_b32_e32 v63, v41, v42
	s_cmpk_lt_i32 s78, 0x121
	s_cbranch_scc1 .Lp2apr0_o0
	v_readlane_b32 s0, v63, 0
	v_readlane_b32 s73, v37, 0
	v_readlane_b32 s78, v61, 15
	v_mov_b32_e32 v231, s0

.Lp2apr1_iter:
	v_sub_u32_e32 v38, v35, v34
	v_or_b32_e32 v41, 1, v38
	v_ffbh_u32_e32 v41, v41
	v_sub_u32_e32 v41, 26, v41
	v_max_i32_e32 v39, 0, v41
	v_mov_b32_e32 v36, 0
	v_or_b32_e32 v42, 32, v36
	v_lshlrev_b32_e32 v41, v39, v42
	v_add_u32_e64 v43, v34, v41 clamp
	v_mov_b32_e32 v44, 0
	v_cmp_ge_u32_e32 vcc, v0, v43
	v_cmp_ge_u32_e64 s[0:1], v1, v43
	v_cmp_ge_u32_e64 s[2:3], v2, v43
	v_addc_co_u32_e64 v44, vcc, 0, v44, vcc
	v_cmp_ge_u32_e32 vcc, v3, v43
	v_addc_co_u32_e64 v44, s[0:1], 0, v44, s[0:1]
	v_cmp_ge_u32_e64 s[0:1], v4, v43
	v_addc_co_u32_e64 v44, s[2:3], 0, v44, s[2:3]
	v_cmp_ge_u32_e64 s[2:3], v5, v43
	v_addc_co_u32_e64 v44, vcc, 0, v44, vcc
	v_cmp_ge_u32_e32 vcc, v6, v43
	v_addc_co_u32_e64 v44, s[0:1], 0, v44, s[0:1]
	v_cmp_ge_u32_e64 s[0:1], v7, v43
	v_addc_co_u32_e64 v44, s[2:3], 0, v44, s[2:3]
	v_cmp_ge_u32_e64 s[2:3], v8, v43
	v_addc_co_u32_e64 v44, vcc, 0, v44, vcc
	v_cmp_ge_u32_e32 vcc, v9, v43
	v_addc_co_u32_e64 v44, s[0:1], 0, v44, s[0:1]
	v_cmp_ge_u32_e64 s[0:1], v10, v43
	v_addc_co_u32_e64 v44, s[2:3], 0, v44, s[2:3]
	v_cmp_ge_u32_e64 s[2:3], v11, v43
	v_addc_co_u32_e64 v44, vcc, 0, v44, vcc
	v_cmp_ge_u32_e32 vcc, v12, v43
	v_addc_co_u32_e64 v44, s[0:1], 0, v44, s[0:1]
	v_cmp_ge_u32_e64 s[0:1], v13, v43
	v_addc_co_u32_e64 v44, s[2:3], 0, v44, s[2:3]
	v_cmp_ge_u32_e64 s[2:3], v14, v43
	v_addc_co_u32_e64 v44, vcc, 0, v44, vcc
	v_cmp_ge_u32_e32 vcc, v15, v43
	v_addc_co_u32_e64 v44, s[0:1], 0, v44, s[0:1]
	v_cmp_ge_u32_e64 s[0:1], v16, v43
	v_addc_co_u32_e64 v44, s[2:3], 0, v44, s[2:3]
	v_cmp_ge_u32_e64 s[2:3], v17, v43
	v_addc_co_u32_e64 v44, vcc, 0, v44, vcc
	v_cmp_ge_u32_e32 vcc, v18, v43
	v_addc_co_u32_e64 v44, s[0:1], 0, v44, s[0:1]
	v_cmp_ge_u32_e64 s[0:1], v19, v43
	v_addc_co_u32_e64 v44, s[2:3], 0, v44, s[2:3]
	v_cmp_ge_u32_e64 s[2:3], v20, v43
	v_addc_co_u32_e64 v44, vcc, 0, v44, vcc
	v_cmp_ge_u32_e32 vcc, v21, v43
	v_addc_co_u32_e64 v44, s[0:1], 0, v44, s[0:1]
	v_cmp_ge_u32_e64 s[0:1], v22, v43
	v_addc_co_u32_e64 v44, s[2:3], 0, v44, s[2:3]
	v_cmp_ge_u32_e64 s[2:3], v23, v43
	v_addc_co_u32_e64 v44, vcc, 0, v44, vcc
	v_cmp_ge_u32_e32 vcc, v24, v43
	v_addc_co_u32_e64 v44, s[0:1], 0, v44, s[0:1]
	v_cmp_ge_u32_e64 s[0:1], v25, v43
	v_addc_co_u32_e64 v44, s[2:3], 0, v44, s[2:3]
	v_cmp_ge_u32_e64 s[2:3], v26, v43
	v_addc_co_u32_e64 v44, vcc, 0, v44, vcc
	v_cmp_ge_u32_e32 vcc, v27, v43
	v_addc_co_u32_e64 v44, s[0:1], 0, v44, s[0:1]
	v_cmp_ge_u32_e64 s[0:1], v28, v43
	v_addc_co_u32_e64 v44, s[2:3], 0, v44, s[2:3]
	v_cmp_ge_u32_e64 s[2:3], v29, v43
	v_addc_co_u32_e64 v44, vcc, 0, v44, vcc
	v_cmp_ge_u32_e32 vcc, v30, v43
	v_addc_co_u32_e64 v44, s[0:1], 0, v44, s[0:1]
	v_cmp_ge_u32_e64 s[0:1], v31, v43
	v_addc_co_u32_e64 v44, s[2:3], 0, v44, s[2:3]
	v_addc_co_u32_e64 v44, vcc, 0, v44, vcc
	v_addc_co_u32_e64 v44, s[0:1], 0, v44, s[0:1]
	v_mov_b32_e32 v45, v44
	s_nop 1
	v_add_u32_dpp v45, v45, v45 row_ror:1 row_mask:0xf bank_mask:0xf
	s_nop 1
	v_add_u32_dpp v45, v45, v45 row_ror:2 row_mask:0xf bank_mask:0xf
	s_nop 1
	v_add_u32_dpp v45, v45, v45 row_ror:4 row_mask:0xf bank_mask:0xf
	s_nop 1
	v_add_u32_dpp v45, v45, v45 row_ror:8 row_mask:0xf bank_mask:0xf
	s_nop 0
	v_cmp_le_u32_e32 vcc, 0x100, v45
	s_nop 1
	v_cndmask_b32_e32 v36, v36, v42, vcc
	v_cndmask_b32_e32 v46, v46, v45, vcc
	v_cndmask_b32_e32 v47, v47, v44, vcc
	v_or_b32_e32 v42, 16, v36
	v_lshlrev_b32_e32 v41, v39, v42
	v_add_u32_e64 v43, v34, v41 clamp
	v_mov_b32_e32 v44, 0
	v_cmp_ge_u32_e32 vcc, v0, v43
	v_cmp_ge_u32_e64 s[0:1], v1, v43
	v_cmp_ge_u32_e64 s[2:3], v2, v43
	v_addc_co_u32_e64 v44, vcc, 0, v44, vcc
	v_cmp_ge_u32_e32 vcc, v3, v43
	v_addc_co_u32_e64 v44, s[0:1], 0, v44, s[0:1]
	v_cmp_ge_u32_e64 s[0:1], v4, v43
	v_addc_co_u32_e64 v44, s[2:3], 0, v44, s[2:3]
	v_cmp_ge_u32_e64 s[2:3], v5, v43
	v_addc_co_u32_e64 v44, vcc, 0, v44, vcc
	v_cmp_ge_u32_e32 vcc, v6, v43
	v_addc_co_u32_e64 v44, s[0:1], 0, v44, s[0:1]
	v_cmp_ge_u32_e64 s[0:1], v7, v43
	v_addc_co_u32_e64 v44, s[2:3], 0, v44, s[2:3]
	v_cmp_ge_u32_e64 s[2:3], v8, v43
	v_addc_co_u32_e64 v44, vcc, 0, v44, vcc
	v_cmp_ge_u32_e32 vcc, v9, v43
	v_addc_co_u32_e64 v44, s[0:1], 0, v44, s[0:1]
	v_cmp_ge_u32_e64 s[0:1], v10, v43
	v_addc_co_u32_e64 v44, s[2:3], 0, v44, s[2:3]
	v_cmp_ge_u32_e64 s[2:3], v11, v43
	v_addc_co_u32_e64 v44, vcc, 0, v44, vcc
	v_cmp_ge_u32_e32 vcc, v12, v43
	v_addc_co_u32_e64 v44, s[0:1], 0, v44, s[0:1]
	v_cmp_ge_u32_e64 s[0:1], v13, v43
	v_addc_co_u32_e64 v44, s[2:3], 0, v44, s[2:3]
	v_cmp_ge_u32_e64 s[2:3], v14, v43
	v_addc_co_u32_e64 v44, vcc, 0, v44, vcc
	v_cmp_ge_u32_e32 vcc, v15, v43
	v_addc_co_u32_e64 v44, s[0:1], 0, v44, s[0:1]
	v_cmp_ge_u32_e64 s[0:1], v16, v43
	v_addc_co_u32_e64 v44, s[2:3], 0, v44, s[2:3]
	v_cmp_ge_u32_e64 s[2:3], v17, v43
	v_addc_co_u32_e64 v44, vcc, 0, v44, vcc
	v_cmp_ge_u32_e32 vcc, v18, v43
	v_addc_co_u32_e64 v44, s[0:1], 0, v44, s[0:1]
	v_cmp_ge_u32_e64 s[0:1], v19, v43
	v_addc_co_u32_e64 v44, s[2:3], 0, v44, s[2:3]
	v_cmp_ge_u32_e64 s[2:3], v20, v43
	v_addc_co_u32_e64 v44, vcc, 0, v44, vcc
	v_cmp_ge_u32_e32 vcc, v21, v43
	v_addc_co_u32_e64 v44, s[0:1], 0, v44, s[0:1]
	v_cmp_ge_u32_e64 s[0:1], v22, v43
	v_addc_co_u32_e64 v44, s[2:3], 0, v44, s[2:3]
	v_cmp_ge_u32_e64 s[2:3], v23, v43
	v_addc_co_u32_e64 v44, vcc, 0, v44, vcc
	v_cmp_ge_u32_e32 vcc, v24, v43
	v_addc_co_u32_e64 v44, s[0:1], 0, v44, s[0:1]
	v_cmp_ge_u32_e64 s[0:1], v25, v43
	v_addc_co_u32_e64 v44, s[2:3], 0, v44, s[2:3]
	v_cmp_ge_u32_e64 s[2:3], v26, v43
	v_addc_co_u32_e64 v44, vcc, 0, v44, vcc
	v_cmp_ge_u32_e32 vcc, v27, v43
	v_addc_co_u32_e64 v44, s[0:1], 0, v44, s[0:1]
	v_cmp_ge_u32_e64 s[0:1], v28, v43
	v_addc_co_u32_e64 v44, s[2:3], 0, v44, s[2:3]
	v_cmp_ge_u32_e64 s[2:3], v29, v43
	v_addc_co_u32_e64 v44, vcc, 0, v44, vcc
	v_cmp_ge_u32_e32 vcc, v30, v43
	v_addc_co_u32_e64 v44, s[0:1], 0, v44, s[0:1]
	v_cmp_ge_u32_e64 s[0:1], v31, v43
	v_addc_co_u32_e64 v44, s[2:3], 0, v44, s[2:3]
	v_addc_co_u32_e64 v44, vcc, 0, v44, vcc
	v_addc_co_u32_e64 v44, s[0:1], 0, v44, s[0:1]
	v_mov_b32_e32 v45, v44
	s_nop 1
	v_add_u32_dpp v45, v45, v45 row_ror:1 row_mask:0xf bank_mask:0xf
	s_nop 1
	v_add_u32_dpp v45, v45, v45 row_ror:2 row_mask:0xf bank_mask:0xf
	s_nop 1
	v_add_u32_dpp v45, v45, v45 row_ror:4 row_mask:0xf bank_mask:0xf
	s_nop 1
	v_add_u32_dpp v45, v45, v45 row_ror:8 row_mask:0xf bank_mask:0xf
	s_nop 0
	v_cmp_le_u32_e32 vcc, 0x100, v45
	s_nop 1
	v_cndmask_b32_e32 v36, v36, v42, vcc
	v_cndmask_b32_e32 v46, v46, v45, vcc
	v_cndmask_b32_e32 v47, v47, v44, vcc
	v_or_b32_e32 v42, 8, v36
	v_lshlrev_b32_e32 v41, v39, v42
	v_add_u32_e64 v43, v34, v41 clamp
	v_mov_b32_e32 v44, 0
	v_cmp_ge_u32_e32 vcc, v0, v43
	v_cmp_ge_u32_e64 s[0:1], v1, v43
	v_cmp_ge_u32_e64 s[2:3], v2, v43
	v_addc_co_u32_e64 v44, vcc, 0, v44, vcc
	v_cmp_ge_u32_e32 vcc, v3, v43
	v_addc_co_u32_e64 v44, s[0:1], 0, v44, s[0:1]
	v_cmp_ge_u32_e64 s[0:1], v4, v43
	v_addc_co_u32_e64 v44, s[2:3], 0, v44, s[2:3]
	v_cmp_ge_u32_e64 s[2:3], v5, v43
	v_addc_co_u32_e64 v44, vcc, 0, v44, vcc
	v_cmp_ge_u32_e32 vcc, v6, v43
	v_addc_co_u32_e64 v44, s[0:1], 0, v44, s[0:1]
	v_cmp_ge_u32_e64 s[0:1], v7, v43
	v_addc_co_u32_e64 v44, s[2:3], 0, v44, s[2:3]
	v_cmp_ge_u32_e64 s[2:3], v8, v43
	v_addc_co_u32_e64 v44, vcc, 0, v44, vcc
	v_cmp_ge_u32_e32 vcc, v9, v43
	v_addc_co_u32_e64 v44, s[0:1], 0, v44, s[0:1]
	v_cmp_ge_u32_e64 s[0:1], v10, v43
	v_addc_co_u32_e64 v44, s[2:3], 0, v44, s[2:3]
	v_cmp_ge_u32_e64 s[2:3], v11, v43
	v_addc_co_u32_e64 v44, vcc, 0, v44, vcc
	v_cmp_ge_u32_e32 vcc, v12, v43
	v_addc_co_u32_e64 v44, s[0:1], 0, v44, s[0:1]
	v_cmp_ge_u32_e64 s[0:1], v13, v43
	v_addc_co_u32_e64 v44, s[2:3], 0, v44, s[2:3]
	v_cmp_ge_u32_e64 s[2:3], v14, v43
	v_addc_co_u32_e64 v44, vcc, 0, v44, vcc
	v_cmp_ge_u32_e32 vcc, v15, v43
	v_addc_co_u32_e64 v44, s[0:1], 0, v44, s[0:1]
	v_cmp_ge_u32_e64 s[0:1], v16, v43
	v_addc_co_u32_e64 v44, s[2:3], 0, v44, s[2:3]
	v_cmp_ge_u32_e64 s[2:3], v17, v43
	v_addc_co_u32_e64 v44, vcc, 0, v44, vcc
	v_cmp_ge_u32_e32 vcc, v18, v43
	v_addc_co_u32_e64 v44, s[0:1], 0, v44, s[0:1]
	v_cmp_ge_u32_e64 s[0:1], v19, v43
	v_addc_co_u32_e64 v44, s[2:3], 0, v44, s[2:3]
	v_cmp_ge_u32_e64 s[2:3], v20, v43
	v_addc_co_u32_e64 v44, vcc, 0, v44, vcc
	v_cmp_ge_u32_e32 vcc, v21, v43
	v_addc_co_u32_e64 v44, s[0:1], 0, v44, s[0:1]
	v_cmp_ge_u32_e64 s[0:1], v22, v43
	v_addc_co_u32_e64 v44, s[2:3], 0, v44, s[2:3]
	v_cmp_ge_u32_e64 s[2:3], v23, v43
	v_addc_co_u32_e64 v44, vcc, 0, v44, vcc
	v_cmp_ge_u32_e32 vcc, v24, v43
	v_addc_co_u32_e64 v44, s[0:1], 0, v44, s[0:1]
	v_cmp_ge_u32_e64 s[0:1], v25, v43
	v_addc_co_u32_e64 v44, s[2:3], 0, v44, s[2:3]
	v_cmp_ge_u32_e64 s[2:3], v26, v43
	v_addc_co_u32_e64 v44, vcc, 0, v44, vcc
	v_cmp_ge_u32_e32 vcc, v27, v43
	v_addc_co_u32_e64 v44, s[0:1], 0, v44, s[0:1]
	v_cmp_ge_u32_e64 s[0:1], v28, v43
	v_addc_co_u32_e64 v44, s[2:3], 0, v44, s[2:3]
	v_cmp_ge_u32_e64 s[2:3], v29, v43
	v_addc_co_u32_e64 v44, vcc, 0, v44, vcc
	v_cmp_ge_u32_e32 vcc, v30, v43
	v_addc_co_u32_e64 v44, s[0:1], 0, v44, s[0:1]
	v_cmp_ge_u32_e64 s[0:1], v31, v43
	v_addc_co_u32_e64 v44, s[2:3], 0, v44, s[2:3]
	v_addc_co_u32_e64 v44, vcc, 0, v44, vcc
	v_addc_co_u32_e64 v44, s[0:1], 0, v44, s[0:1]
	v_mov_b32_e32 v45, v44
	s_nop 1
	v_add_u32_dpp v45, v45, v45 row_ror:1 row_mask:0xf bank_mask:0xf
	s_nop 1
	v_add_u32_dpp v45, v45, v45 row_ror:2 row_mask:0xf bank_mask:0xf
	s_nop 1
	v_add_u32_dpp v45, v45, v45 row_ror:4 row_mask:0xf bank_mask:0xf
	s_nop 1
	v_add_u32_dpp v45, v45, v45 row_ror:8 row_mask:0xf bank_mask:0xf
	s_nop 0
	v_cmp_le_u32_e32 vcc, 0x100, v45
	s_nop 1
	v_cndmask_b32_e32 v36, v36, v42, vcc
	v_cndmask_b32_e32 v46, v46, v45, vcc
	v_cndmask_b32_e32 v47, v47, v44, vcc
	v_or_b32_e32 v42, 4, v36
	v_lshlrev_b32_e32 v41, v39, v42
	v_add_u32_e64 v43, v34, v41 clamp
	v_mov_b32_e32 v44, 0
	v_cmp_ge_u32_e32 vcc, v0, v43
	v_cmp_ge_u32_e64 s[0:1], v1, v43
	v_cmp_ge_u32_e64 s[2:3], v2, v43
	v_addc_co_u32_e64 v44, vcc, 0, v44, vcc
	v_cmp_ge_u32_e32 vcc, v3, v43
	v_addc_co_u32_e64 v44, s[0:1], 0, v44, s[0:1]
	v_cmp_ge_u32_e64 s[0:1], v4, v43
	v_addc_co_u32_e64 v44, s[2:3], 0, v44, s[2:3]
	v_cmp_ge_u32_e64 s[2:3], v5, v43
	v_addc_co_u32_e64 v44, vcc, 0, v44, vcc
	v_cmp_ge_u32_e32 vcc, v6, v43
	v_addc_co_u32_e64 v44, s[0:1], 0, v44, s[0:1]
	v_cmp_ge_u32_e64 s[0:1], v7, v43
	v_addc_co_u32_e64 v44, s[2:3], 0, v44, s[2:3]
	v_cmp_ge_u32_e64 s[2:3], v8, v43
	v_addc_co_u32_e64 v44, vcc, 0, v44, vcc
	v_cmp_ge_u32_e32 vcc, v9, v43
	v_addc_co_u32_e64 v44, s[0:1], 0, v44, s[0:1]
	v_cmp_ge_u32_e64 s[0:1], v10, v43
	v_addc_co_u32_e64 v44, s[2:3], 0, v44, s[2:3]
	v_cmp_ge_u32_e64 s[2:3], v11, v43
	v_addc_co_u32_e64 v44, vcc, 0, v44, vcc
	v_cmp_ge_u32_e32 vcc, v12, v43
	v_addc_co_u32_e64 v44, s[0:1], 0, v44, s[0:1]
	v_cmp_ge_u32_e64 s[0:1], v13, v43
	v_addc_co_u32_e64 v44, s[2:3], 0, v44, s[2:3]
	v_cmp_ge_u32_e64 s[2:3], v14, v43
	v_addc_co_u32_e64 v44, vcc, 0, v44, vcc
	v_cmp_ge_u32_e32 vcc, v15, v43
	v_addc_co_u32_e64 v44, s[0:1], 0, v44, s[0:1]
	v_cmp_ge_u32_e64 s[0:1], v16, v43
	v_addc_co_u32_e64 v44, s[2:3], 0, v44, s[2:3]
	v_cmp_ge_u32_e64 s[2:3], v17, v43
	v_addc_co_u32_e64 v44, vcc, 0, v44, vcc
	v_cmp_ge_u32_e32 vcc, v18, v43
	v_addc_co_u32_e64 v44, s[0:1], 0, v44, s[0:1]
	v_cmp_ge_u32_e64 s[0:1], v19, v43
	v_addc_co_u32_e64 v44, s[2:3], 0, v44, s[2:3]
	v_cmp_ge_u32_e64 s[2:3], v20, v43
	v_addc_co_u32_e64 v44, vcc, 0, v44, vcc
	v_cmp_ge_u32_e32 vcc, v21, v43
	v_addc_co_u32_e64 v44, s[0:1], 0, v44, s[0:1]
	v_cmp_ge_u32_e64 s[0:1], v22, v43
	v_addc_co_u32_e64 v44, s[2:3], 0, v44, s[2:3]
	v_cmp_ge_u32_e64 s[2:3], v23, v43
	v_addc_co_u32_e64 v44, vcc, 0, v44, vcc
	v_cmp_ge_u32_e32 vcc, v24, v43
	v_addc_co_u32_e64 v44, s[0:1], 0, v44, s[0:1]
	v_cmp_ge_u32_e64 s[0:1], v25, v43
	v_addc_co_u32_e64 v44, s[2:3], 0, v44, s[2:3]
	v_cmp_ge_u32_e64 s[2:3], v26, v43
	v_addc_co_u32_e64 v44, vcc, 0, v44, vcc
	v_cmp_ge_u32_e32 vcc, v27, v43
	v_addc_co_u32_e64 v44, s[0:1], 0, v44, s[0:1]
	v_cmp_ge_u32_e64 s[0:1], v28, v43
	v_addc_co_u32_e64 v44, s[2:3], 0, v44, s[2:3]
	v_cmp_ge_u32_e64 s[2:3], v29, v43
	v_addc_co_u32_e64 v44, vcc, 0, v44, vcc
	v_cmp_ge_u32_e32 vcc, v30, v43
	v_addc_co_u32_e64 v44, s[0:1], 0, v44, s[0:1]
	v_cmp_ge_u32_e64 s[0:1], v31, v43
	v_addc_co_u32_e64 v44, s[2:3], 0, v44, s[2:3]
	v_addc_co_u32_e64 v44, vcc, 0, v44, vcc
	v_addc_co_u32_e64 v44, s[0:1], 0, v44, s[0:1]
	v_mov_b32_e32 v45, v44
	s_nop 1
	v_add_u32_dpp v45, v45, v45 row_ror:1 row_mask:0xf bank_mask:0xf
	s_nop 1
	v_add_u32_dpp v45, v45, v45 row_ror:2 row_mask:0xf bank_mask:0xf
	s_nop 1
	v_add_u32_dpp v45, v45, v45 row_ror:4 row_mask:0xf bank_mask:0xf
	s_nop 1
	v_add_u32_dpp v45, v45, v45 row_ror:8 row_mask:0xf bank_mask:0xf
	s_nop 0
	v_cmp_le_u32_e32 vcc, 0x100, v45
	s_nop 1
	v_cndmask_b32_e32 v36, v36, v42, vcc
	v_cndmask_b32_e32 v46, v46, v45, vcc
	v_cndmask_b32_e32 v47, v47, v44, vcc
	v_or_b32_e32 v42, 2, v36
	v_lshlrev_b32_e32 v41, v39, v42
	v_add_u32_e64 v43, v34, v41 clamp
	v_mov_b32_e32 v44, 0
	v_cmp_ge_u32_e32 vcc, v0, v43
	v_cmp_ge_u32_e64 s[0:1], v1, v43
	v_cmp_ge_u32_e64 s[2:3], v2, v43
	v_addc_co_u32_e64 v44, vcc, 0, v44, vcc
	v_cmp_ge_u32_e32 vcc, v3, v43
	v_addc_co_u32_e64 v44, s[0:1], 0, v44, s[0:1]
	v_cmp_ge_u32_e64 s[0:1], v4, v43
	v_addc_co_u32_e64 v44, s[2:3], 0, v44, s[2:3]
	v_cmp_ge_u32_e64 s[2:3], v5, v43
	v_addc_co_u32_e64 v44, vcc, 0, v44, vcc
	v_cmp_ge_u32_e32 vcc, v6, v43
	v_addc_co_u32_e64 v44, s[0:1], 0, v44, s[0:1]
	v_cmp_ge_u32_e64 s[0:1], v7, v43
	v_addc_co_u32_e64 v44, s[2:3], 0, v44, s[2:3]
	v_cmp_ge_u32_e64 s[2:3], v8, v43
	v_addc_co_u32_e64 v44, vcc, 0, v44, vcc
	v_cmp_ge_u32_e32 vcc, v9, v43
	v_addc_co_u32_e64 v44, s[0:1], 0, v44, s[0:1]
	v_cmp_ge_u32_e64 s[0:1], v10, v43
	v_addc_co_u32_e64 v44, s[2:3], 0, v44, s[2:3]
	v_cmp_ge_u32_e64 s[2:3], v11, v43
	v_addc_co_u32_e64 v44, vcc, 0, v44, vcc
	v_cmp_ge_u32_e32 vcc, v12, v43
	v_addc_co_u32_e64 v44, s[0:1], 0, v44, s[0:1]
	v_cmp_ge_u32_e64 s[0:1], v13, v43
	v_addc_co_u32_e64 v44, s[2:3], 0, v44, s[2:3]
	v_cmp_ge_u32_e64 s[2:3], v14, v43
	v_addc_co_u32_e64 v44, vcc, 0, v44, vcc
	v_cmp_ge_u32_e32 vcc, v15, v43
	v_addc_co_u32_e64 v44, s[0:1], 0, v44, s[0:1]
	v_cmp_ge_u32_e64 s[0:1], v16, v43
	v_addc_co_u32_e64 v44, s[2:3], 0, v44, s[2:3]
	v_cmp_ge_u32_e64 s[2:3], v17, v43
	v_addc_co_u32_e64 v44, vcc, 0, v44, vcc
	v_cmp_ge_u32_e32 vcc, v18, v43
	v_addc_co_u32_e64 v44, s[0:1], 0, v44, s[0:1]
	v_cmp_ge_u32_e64 s[0:1], v19, v43
	v_addc_co_u32_e64 v44, s[2:3], 0, v44, s[2:3]
	v_cmp_ge_u32_e64 s[2:3], v20, v43
	v_addc_co_u32_e64 v44, vcc, 0, v44, vcc
	v_cmp_ge_u32_e32 vcc, v21, v43
	v_addc_co_u32_e64 v44, s[0:1], 0, v44, s[0:1]
	v_cmp_ge_u32_e64 s[0:1], v22, v43
	v_addc_co_u32_e64 v44, s[2:3], 0, v44, s[2:3]
	v_cmp_ge_u32_e64 s[2:3], v23, v43
	v_addc_co_u32_e64 v44, vcc, 0, v44, vcc
	v_cmp_ge_u32_e32 vcc, v24, v43
	v_addc_co_u32_e64 v44, s[0:1], 0, v44, s[0:1]
	v_cmp_ge_u32_e64 s[0:1], v25, v43
	v_addc_co_u32_e64 v44, s[2:3], 0, v44, s[2:3]
	v_cmp_ge_u32_e64 s[2:3], v26, v43
	v_addc_co_u32_e64 v44, vcc, 0, v44, vcc
	v_cmp_ge_u32_e32 vcc, v27, v43
	v_addc_co_u32_e64 v44, s[0:1], 0, v44, s[0:1]
	v_cmp_ge_u32_e64 s[0:1], v28, v43
	v_addc_co_u32_e64 v44, s[2:3], 0, v44, s[2:3]
	v_cmp_ge_u32_e64 s[2:3], v29, v43
	v_addc_co_u32_e64 v44, vcc, 0, v44, vcc
	v_cmp_ge_u32_e32 vcc, v30, v43
	v_addc_co_u32_e64 v44, s[0:1], 0, v44, s[0:1]
	v_cmp_ge_u32_e64 s[0:1], v31, v43
	v_addc_co_u32_e64 v44, s[2:3], 0, v44, s[2:3]
	v_addc_co_u32_e64 v44, vcc, 0, v44, vcc
	v_addc_co_u32_e64 v44, s[0:1], 0, v44, s[0:1]
	v_mov_b32_e32 v45, v44
	s_nop 1
	v_add_u32_dpp v45, v45, v45 row_ror:1 row_mask:0xf bank_mask:0xf
	s_nop 1
	v_add_u32_dpp v45, v45, v45 row_ror:2 row_mask:0xf bank_mask:0xf
	s_nop 1
	v_add_u32_dpp v45, v45, v45 row_ror:4 row_mask:0xf bank_mask:0xf
	s_nop 1
	v_add_u32_dpp v45, v45, v45 row_ror:8 row_mask:0xf bank_mask:0xf
	s_nop 0
	v_cmp_le_u32_e32 vcc, 0x100, v45
	s_nop 1
	v_cndmask_b32_e32 v36, v36, v42, vcc
	v_cndmask_b32_e32 v46, v46, v45, vcc
	v_cndmask_b32_e32 v47, v47, v44, vcc
	v_or_b32_e32 v42, 1, v36
	v_lshlrev_b32_e32 v41, v39, v42
	v_add_u32_e64 v43, v34, v41 clamp
	v_mov_b32_e32 v44, 0
	v_cmp_ge_u32_e32 vcc, v0, v43
	v_cmp_ge_u32_e64 s[0:1], v1, v43
	v_cmp_ge_u32_e64 s[2:3], v2, v43
	v_addc_co_u32_e64 v44, vcc, 0, v44, vcc
	v_cmp_ge_u32_e32 vcc, v3, v43
	v_addc_co_u32_e64 v44, s[0:1], 0, v44, s[0:1]
	v_cmp_ge_u32_e64 s[0:1], v4, v43
	v_addc_co_u32_e64 v44, s[2:3], 0, v44, s[2:3]
	v_cmp_ge_u32_e64 s[2:3], v5, v43
	v_addc_co_u32_e64 v44, vcc, 0, v44, vcc
	v_cmp_ge_u32_e32 vcc, v6, v43
	v_addc_co_u32_e64 v44, s[0:1], 0, v44, s[0:1]
	v_cmp_ge_u32_e64 s[0:1], v7, v43
	v_addc_co_u32_e64 v44, s[2:3], 0, v44, s[2:3]
	v_cmp_ge_u32_e64 s[2:3], v8, v43
	v_addc_co_u32_e64 v44, vcc, 0, v44, vcc
	v_cmp_ge_u32_e32 vcc, v9, v43
	v_addc_co_u32_e64 v44, s[0:1], 0, v44, s[0:1]
	v_cmp_ge_u32_e64 s[0:1], v10, v43
	v_addc_co_u32_e64 v44, s[2:3], 0, v44, s[2:3]
	v_cmp_ge_u32_e64 s[2:3], v11, v43
	v_addc_co_u32_e64 v44, vcc, 0, v44, vcc
	v_cmp_ge_u32_e32 vcc, v12, v43
	v_addc_co_u32_e64 v44, s[0:1], 0, v44, s[0:1]
	v_cmp_ge_u32_e64 s[0:1], v13, v43
	v_addc_co_u32_e64 v44, s[2:3], 0, v44, s[2:3]
	v_cmp_ge_u32_e64 s[2:3], v14, v43
	v_addc_co_u32_e64 v44, vcc, 0, v44, vcc
	v_cmp_ge_u32_e32 vcc, v15, v43
	v_addc_co_u32_e64 v44, s[0:1], 0, v44, s[0:1]
	v_cmp_ge_u32_e64 s[0:1], v16, v43
	v_addc_co_u32_e64 v44, s[2:3], 0, v44, s[2:3]
	v_cmp_ge_u32_e64 s[2:3], v17, v43
	v_addc_co_u32_e64 v44, vcc, 0, v44, vcc
	v_cmp_ge_u32_e32 vcc, v18, v43
	v_addc_co_u32_e64 v44, s[0:1], 0, v44, s[0:1]
	v_cmp_ge_u32_e64 s[0:1], v19, v43
	v_addc_co_u32_e64 v44, s[2:3], 0, v44, s[2:3]
	v_cmp_ge_u32_e64 s[2:3], v20, v43
	v_addc_co_u32_e64 v44, vcc, 0, v44, vcc
	v_cmp_ge_u32_e32 vcc, v21, v43
	v_addc_co_u32_e64 v44, s[0:1], 0, v44, s[0:1]
	v_cmp_ge_u32_e64 s[0:1], v22, v43
	v_addc_co_u32_e64 v44, s[2:3], 0, v44, s[2:3]
	v_cmp_ge_u32_e64 s[2:3], v23, v43
	v_addc_co_u32_e64 v44, vcc, 0, v44, vcc
	v_cmp_ge_u32_e32 vcc, v24, v43
	v_addc_co_u32_e64 v44, s[0:1], 0, v44, s[0:1]
	v_cmp_ge_u32_e64 s[0:1], v25, v43
	v_addc_co_u32_e64 v44, s[2:3], 0, v44, s[2:3]
	v_cmp_ge_u32_e64 s[2:3], v26, v43
	v_addc_co_u32_e64 v44, vcc, 0, v44, vcc
	v_cmp_ge_u32_e32 vcc, v27, v43
	v_addc_co_u32_e64 v44, s[0:1], 0, v44, s[0:1]
	v_cmp_ge_u32_e64 s[0:1], v28, v43
	v_addc_co_u32_e64 v44, s[2:3], 0, v44, s[2:3]
	v_cmp_ge_u32_e64 s[2:3], v29, v43
	v_addc_co_u32_e64 v44, vcc, 0, v44, vcc
	v_cmp_ge_u32_e32 vcc, v30, v43
	v_addc_co_u32_e64 v44, s[0:1], 0, v44, s[0:1]
	v_cmp_ge_u32_e64 s[0:1], v31, v43
	v_addc_co_u32_e64 v44, s[2:3], 0, v44, s[2:3]
	v_addc_co_u32_e64 v44, vcc, 0, v44, vcc
	v_addc_co_u32_e64 v44, s[0:1], 0, v44, s[0:1]
	v_mov_b32_e32 v45, v44
	s_nop 1
	v_add_u32_dpp v45, v45, v45 row_ror:1 row_mask:0xf bank_mask:0xf
	s_nop 1
	v_add_u32_dpp v45, v45, v45 row_ror:2 row_mask:0xf bank_mask:0xf
	s_nop 1
	v_add_u32_dpp v45, v45, v45 row_ror:4 row_mask:0xf bank_mask:0xf
	s_nop 1
	v_add_u32_dpp v45, v45, v45 row_ror:8 row_mask:0xf bank_mask:0xf
	s_nop 0
	v_cmp_le_u32_e32 vcc, 0x100, v45
	s_nop 1
	v_cndmask_b32_e32 v36, v36, v42, vcc
	v_cndmask_b32_e32 v46, v46, v45, vcc
	v_cndmask_b32_e32 v47, v47, v44, vcc
	v_lshlrev_b32_e32 v41, v39, v36
	v_add_u32_e32 v41, v34, v41
	v_cmp_ge_u32_e32 vcc, 0x120, v46
	v_cmp_eq_u32_e64 s[0:1], 0, v39
	v_lshlrev_b32_e32 v42, v39, v200
	v_add_u32_e32 v42, -1, v42
	s_or_b64 vcc, vcc, s[0:1]
	s_andn2_b64 s[0:1], vcc, s[50:51]
	s_nor_b64 s[2:3], vcc, s[50:51]
	s_or_b64 s[50:51], s[50:51], vcc
	v_add_u32_e64 v42, v41, v42 clamp
	v_min_u32_e32 v42, v42, v35
	v_cndmask_b32_e64 v37, v37, v41, s[0:1]
	v_cndmask_b32_e64 v62, v62, v47, s[0:1]
	v_cndmask_b32_e64 v35, v35, v42, s[2:3]
	v_cndmask_b32_e64 v34, v34, v41, s[2:3]
	s_cmp_eq_u64 s[50:51], -1
	s_cbranch_scc0 .Lp2apr1_iter
	s_mov_b64 exec, s[22:23]
	v_mov_b32_e32 v61, v62
	s_nop 1
	v_add_u32_dpp v61, v61, v61 row_shr:1 row_mask:0xf bank_mask:0xf bound_ctrl:1
	s_nop 1
	v_add_u32_dpp v61, v61, v61 row_shr:2 row_mask:0xf bank_mask:0xf bound_ctrl:1
	s_nop 1
	v_add_u32_dpp v61, v61, v61 row_shr:4 row_mask:0xf bank_mask:0xf bound_ctrl:1
	s_nop 1
	v_add_u32_dpp v61, v61, v61 row_shr:8 row_mask:0xf bank_mask:0xf bound_ctrl:1
	v_sub_u32_e32 v62, v61, v62
	v_lshl_add_u32 v41, v62, 2, v59
	v_cmpx_ge_u32_e32 vcc, v0, v37
	v_add_u32_e32 v62, 1, v62
	ds_write_b32 v41, v0
	s_mov_b64 exec, s[22:23]
	v_lshl_add_u32 v41, v62, 2, v59
	v_cmpx_ge_u32_e32 vcc, v1, v37
	v_add_u32_e32 v62, 1, v62
	ds_write_b32 v41, v1
	s_mov_b64 exec, s[22:23]
	v_lshl_add_u32 v41, v62, 2, v59
	v_cmpx_ge_u32_e32 vcc, v2, v37
	v_add_u32_e32 v62, 1, v62
	ds_write_b32 v41, v2
	s_mov_b64 exec, s[22:23]
	v_lshl_add_u32 v41, v62, 2, v59
	v_cmpx_ge_u32_e32 vcc, v3, v37
	v_add_u32_e32 v62, 1, v62
	ds_write_b32 v41, v3
	s_mov_b64 exec, s[22:23]
	v_lshl_add_u32 v41, v62, 2, v59
	v_cmpx_ge_u32_e32 vcc, v4, v37
	v_add_u32_e32 v62, 1, v62
	ds_write_b32 v41, v4
	s_mov_b64 exec, s[22:23]
	v_lshl_add_u32 v41, v62, 2, v59
	v_cmpx_ge_u32_e32 vcc, v5, v37
	v_add_u32_e32 v62, 1, v62
	ds_write_b32 v41, v5
	s_mov_b64 exec, s[22:23]
	v_lshl_add_u32 v41, v62, 2, v59
	v_cmpx_ge_u32_e32 vcc, v6, v37
	v_add_u32_e32 v62, 1, v62
	ds_write_b32 v41, v6
	s_mov_b64 exec, s[22:23]
	v_lshl_add_u32 v41, v62, 2, v59
	v_cmpx_ge_u32_e32 vcc, v7, v37
	v_add_u32_e32 v62, 1, v62
	ds_write_b32 v41, v7
	s_mov_b64 exec, s[22:23]
	v_lshl_add_u32 v41, v62, 2, v59
	v_cmpx_ge_u32_e32 vcc, v8, v37
	v_add_u32_e32 v62, 1, v62
	ds_write_b32 v41, v8
	s_mov_b64 exec, s[22:23]
	v_lshl_add_u32 v41, v62, 2, v59
	v_cmpx_ge_u32_e32 vcc, v9, v37
	v_add_u32_e32 v62, 1, v62
	ds_write_b32 v41, v9
	s_mov_b64 exec, s[22:23]
	v_lshl_add_u32 v41, v62, 2, v59
	v_cmpx_ge_u32_e32 vcc, v10, v37
	v_add_u32_e32 v62, 1, v62
	ds_write_b32 v41, v10
	s_mov_b64 exec, s[22:23]
	v_lshl_add_u32 v41, v62, 2, v59
	v_cmpx_ge_u32_e32 vcc, v11, v37
	v_add_u32_e32 v62, 1, v62
	ds_write_b32 v41, v11
	s_mov_b64 exec, s[22:23]
	v_lshl_add_u32 v41, v62, 2, v59
	v_cmpx_ge_u32_e32 vcc, v12, v37
	v_add_u32_e32 v62, 1, v62
	ds_write_b32 v41, v12
	s_mov_b64 exec, s[22:23]
	v_lshl_add_u32 v41, v62, 2, v59
	v_cmpx_ge_u32_e32 vcc, v13, v37
	v_add_u32_e32 v62, 1, v62
	ds_write_b32 v41, v13
	s_mov_b64 exec, s[22:23]
	v_lshl_add_u32 v41, v62, 2, v59
	v_cmpx_ge_u32_e32 vcc, v14, v37
	v_add_u32_e32 v62, 1, v62
	ds_write_b32 v41, v14
	s_mov_b64 exec, s[22:23]
	v_lshl_add_u32 v41, v62, 2, v59
	v_cmpx_ge_u32_e32 vcc, v15, v37
	v_add_u32_e32 v62, 1, v62
	ds_write_b32 v41, v15
	s_mov_b64 exec, s[22:23]
	v_lshl_add_u32 v41, v62, 2, v59
	v_cmpx_ge_u32_e32 vcc, v16, v37
	v_add_u32_e32 v62, 1, v62
	ds_write_b32 v41, v16
	s_mov_b64 exec, s[22:23]
	v_lshl_add_u32 v41, v62, 2, v59
	v_cmpx_ge_u32_e32 vcc, v17, v37
	v_add_u32_e32 v62, 1, v62
	ds_write_b32 v41, v17
	s_mov_b64 exec, s[22:23]
	v_lshl_add_u32 v41, v62, 2, v59
	v_cmpx_ge_u32_e32 vcc, v18, v37
	v_add_u32_e32 v62, 1, v62
	ds_write_b32 v41, v18
	s_mov_b64 exec, s[22:23]
	v_lshl_add_u32 v41, v62, 2, v59
	v_cmpx_ge_u32_e32 vcc, v19, v37
	v_add_u32_e32 v62, 1, v62
	ds_write_b32 v41, v19
	s_mov_b64 exec, s[22:23]
	v_lshl_add_u32 v41, v62, 2, v59
	v_cmpx_ge_u32_e32 vcc, v20, v37
	v_add_u32_e32 v62, 1, v62
	ds_write_b32 v41, v20
	s_mov_b64 exec, s[22:23]
	v_lshl_add_u32 v41, v62, 2, v59
	v_cmpx_ge_u32_e32 vcc, v21, v37
	v_add_u32_e32 v62, 1, v62
	ds_write_b32 v41, v21
	s_mov_b64 exec, s[22:23]
	v_lshl_add_u32 v41, v62, 2, v59
	v_cmpx_ge_u32_e32 vcc, v22, v37
	v_add_u32_e32 v62, 1, v62
	ds_write_b32 v41, v22
	s_mov_b64 exec, s[22:23]
	v_lshl_add_u32 v41, v62, 2, v59
	v_cmpx_ge_u32_e32 vcc, v23, v37
	v_add_u32_e32 v62, 1, v62
	ds_write_b32 v41, v23
	s_mov_b64 exec, s[22:23]
	v_lshl_add_u32 v41, v62, 2, v59
	v_cmpx_ge_u32_e32 vcc, v24, v37
	v_add_u32_e32 v62, 1, v62
	ds_write_b32 v41, v24
	s_mov_b64 exec, s[22:23]
	v_lshl_add_u32 v41, v62, 2, v59
	v_cmpx_ge_u32_e32 vcc, v25, v37
	v_add_u32_e32 v62, 1, v62
	ds_write_b32 v41, v25
	s_mov_b64 exec, s[22:23]
	v_lshl_add_u32 v41, v62, 2, v59
	v_cmpx_ge_u32_e32 vcc, v26, v37
	v_add_u32_e32 v62, 1, v62
	ds_write_b32 v41, v26
	s_mov_b64 exec, s[22:23]
	v_lshl_add_u32 v41, v62, 2, v59
	v_cmpx_ge_u32_e32 vcc, v27, v37
	v_add_u32_e32 v62, 1, v62
	ds_write_b32 v41, v27
	s_mov_b64 exec, s[22:23]
	v_lshl_add_u32 v41, v62, 2, v59
	v_cmpx_ge_u32_e32 vcc, v28, v37
	v_add_u32_e32 v62, 1, v62
	ds_write_b32 v41, v28
	s_mov_b64 exec, s[22:23]
	v_lshl_add_u32 v41, v62, 2, v59
	v_cmpx_ge_u32_e32 vcc, v29, v37
	v_add_u32_e32 v62, 1, v62
	ds_write_b32 v41, v29
	s_mov_b64 exec, s[22:23]
	v_lshl_add_u32 v41, v62, 2, v59
	v_cmpx_ge_u32_e32 vcc, v30, v37
	v_add_u32_e32 v62, 1, v62
	ds_write_b32 v41, v30
	s_mov_b64 exec, s[22:23]
	v_lshl_add_u32 v41, v62, 2, v59
	v_cmpx_ge_u32_e32 vcc, v31, v37
	v_add_u32_e32 v62, 1, v62
	ds_write_b32 v41, v31
	s_mov_b64 exec, s[22:23]
	s_mov_b64 exec, -1
	v_and_b32_e32 v41, 0xffffe000, v37
	v_ashrrev_i32_e32 v42, 31, v41
	v_not_b32_e32 v42, v42
	v_or_b32_e32 v42, 0x80000000, v42
	v_xor_b32_e32 v63, v41, v42
	s_cmpk_lt_i32 s8, 0x121
	s_cbranch_scc1 .Lp2apr1_o0
	v_readlane_b32 s0, v63, 0
	v_readlane_b32 s74, v37, 0
	v_readlane_b32 s8, v61, 15
	v_mov_b32_e32 v233, s0
